# final-LayerNorm f32 output stores marked nt (streamed result, not re-read soon) on top of the nt GEMM epilogues
# speedup vs baseline: 1.0013x; 1.0013x over previous
; DI float bflo(unsigned v) { return __uint_as_float(v << 16); }
; DI float bfhi(unsigned v) { return __uint_as_float(v & 0xffff0000u); }
; DI void phase_lnf(const Params& p, int l, int tid) {
;     ...
;     const int b = row / SEQA, pos = row % SEQA;
;     if (!(l == 1 && pos < CTXL)) {
;       float* dst = (pos < CTXL) ? p.ctxV + ((size_t)b * CTXL + pos) * 1024 : p.out + ((size_t)b * SEQ + pos - CTXL) * 1024;
; #pragma unroll
;       for (int j = 0; j < 4; j++) {
;         v[j].x = ALPHA * v[j].x + bflo(ov[j].x); v[j].y = ALPHA * v[j].y + bfhi(ov[j].x);
;         v[j].z = ALPHA * v[j].z + bflo(ov[j].y); v[j].w = ALPHA * v[j].w + bfhi(ov[j].y);
;       }
;       float mean, rstd; ln_stats(v, mean, rstd);
; #pragma unroll
;       for (int j = 0; j < 4; j++) {
;         const int col = 4 * (lane + 64 * j);
;         float4 g = *(const float4*)(p.lng + l * 1024 + col), bb = *(const float4*)(p.lnb + l * 1024 + col);
;         v[j].x = (v[j].x - mean) * rstd * g.x + bb.x; v[j].y = (v[j].y - mean) * rstd * g.y + bb.y;
;         v[j].z = (v[j].z - mean) * rstd * g.z + bb.z; v[j].w = (v[j].w - mean) * rstd * g.w + bb.w;
;         if (pos >= CTXL) *(float4*)(dst + col) = v[j];
;       }
.LBB0_1314:
	s_or_b64 exec, exec, s[6:7]
	s_movk_i32 s2, 0xff
	s_waitcnt vmcnt(3)
	v_lshlrev_b32_e32 v82, 16, v68
	v_and_b32_e32 v83, 0xffff0000, v68
	v_lshlrev_b32_e32 v84, 16, v69
	v_and_b32_e32 v85, 0xffff0000, v69
	v_lshlrev_b32_e32 v86, 16, v66
	v_and_b32_e32 v87, 0xffff0000, v66
	v_lshlrev_b32_e32 v88, 16, v67
	v_and_b32_e32 v89, 0xffff0000, v67
	v_cmp_lt_i32_e32 vcc, s2, v76
	global_load_dwordx4 v[66:69], v[38:39], off
	global_load_dwordx4 v[76:79], v[40:41], off
	s_waitcnt vmcnt(4)
	v_lshlrev_b32_e32 v80, 16, v70
	v_and_b32_e32 v81, 0xffff0000, v70
	v_lshlrev_b32_e32 v70, 16, v71
	v_and_b32_e32 v71, 0xffff0000, v71
	s_waitcnt vmcnt(2)
	v_pk_fma_f32 v[30:31], v[30:31], s[22:23], v[80:81] op_sel_hi:[1,0,1]
	v_pk_fma_f32 v[32:33], v[32:33], s[22:23], v[70:71] op_sel_hi:[1,0,1]
	v_add_f32_e32 v0, v30, v31
	v_pk_fma_f32 v[26:27], v[26:27], s[22:23], v[82:83] op_sel_hi:[1,0,1]
	v_add_f32_e32 v0, v0, v32
	v_pk_fma_f32 v[28:29], v[28:29], s[22:23], v[84:85] op_sel_hi:[1,0,1]
	v_add_f32_e32 v37, v26, v27
	v_pk_fma_f32 v[80:81], v[22:23], s[22:23], v[86:87] op_sel_hi:[1,0,1]
	v_add_f32_e32 v0, v33, v0
	v_add_f32_e32 v37, v37, v28
	v_pk_fma_f32 v[70:71], v[24:25], s[22:23], v[88:89] op_sel_hi:[1,0,1]
	v_add_f32_e32 v22, v80, v81
	v_lshlrev_b32_e32 v90, 16, v64
	v_and_b32_e32 v91, 0xffff0000, v64
	v_add_f32_e32 v0, 0, v0
	v_add_f32_e32 v37, v29, v37
	v_add_f32_e32 v22, v22, v70
	v_lshlrev_b32_e32 v64, 16, v65
	v_and_b32_e32 v65, 0xffff0000, v65
	v_add_f32_e32 v0, v37, v0
	v_add_f32_e32 v22, v71, v22
	v_pk_fma_f32 v[18:19], v[18:19], s[22:23], v[90:91] op_sel_hi:[1,0,1]
	v_add_f32_e32 v0, v22, v0
	v_pk_fma_f32 v[20:21], v[20:21], s[22:23], v[64:65] op_sel_hi:[1,0,1]
	v_add_f32_e32 v22, v18, v19
	v_add_f32_e32 v22, v22, v20
	v_add_f32_e32 v22, v21, v22
	v_add_f32_e32 v0, v22, v0
	s_mov_b32 s2, 0x800000
	s_nop 0
	v_add_f32_dpp v0, v0, v0 quad_perm:[1,0,3,2] row_mask:0xf bank_mask:0xf bound_ctrl:1
	s_nop 1
	v_add_f32_dpp v0, v0, v0 quad_perm:[2,3,0,1] row_mask:0xf bank_mask:0xf bound_ctrl:1
	s_nop 1
	v_add_f32_dpp v0, v0, v0 row_half_mirror row_mask:0xf bank_mask:0xf bound_ctrl:1
	s_nop 1
	v_add_f32_dpp v0, v0, v0 row_mirror row_mask:0xf bank_mask:0xf bound_ctrl:1
	v_mov_b32_e32 v22, v0
	s_nop 1
	v_permlane16_swap_b32_e32 v0, v22
	v_add_f32_e32 v0, v0, v22
	v_mov_b32_e32 v22, v0
	s_nop 1
	v_permlane32_swap_b32_e32 v0, v22
	v_add_f32_e32 v0, v0, v22
	v_mul_f32_e32 v0, 0x3a800000, v0
	v_pk_add_f32 v[82:83], v[30:31], v[0:1] op_sel_hi:[1,0] neg_lo:[0,1] neg_hi:[0,1]
	v_pk_add_f32 v[24:25], v[26:27], v[0:1] op_sel_hi:[1,0] neg_lo:[0,1] neg_hi:[0,1]
	v_pk_add_f32 v[84:85], v[32:33], v[0:1] op_sel_hi:[1,0] neg_lo:[0,1] neg_hi:[0,1]
	v_pk_mul_f32 v[64:65], v[82:83], v[82:83]
	v_pk_add_f32 v[22:23], v[28:29], v[0:1] op_sel_hi:[1,0] neg_lo:[0,1] neg_hi:[0,1]
	v_pk_mul_f32 v[88:89], v[24:25], v[24:25]
	v_pk_mul_f32 v[86:87], v[84:85], v[84:85]
	v_pk_mul_f32 v[90:91], v[22:23], v[22:23]
	v_pk_add_f32 v[28:29], v[80:81], v[0:1] op_sel_hi:[1,0] neg_lo:[0,1] neg_hi:[0,1]
	v_pk_add_f32 v[26:27], v[70:71], v[0:1] op_sel_hi:[1,0] neg_lo:[0,1] neg_hi:[0,1]
	v_pk_add_f32 v[32:33], v[18:19], v[0:1] op_sel_hi:[1,0] neg_lo:[0,1] neg_hi:[0,1]
	v_pk_add_f32 v[30:31], v[20:21], v[0:1] op_sel_hi:[1,0] neg_lo:[0,1] neg_hi:[0,1]
	v_add_f32_e32 v0, v88, v89
	v_add_f32_e32 v37, v64, v65
	v_add_f32_e32 v0, v90, v0
	v_add_f32_e32 v37, v86, v37
	v_pk_mul_f32 v[70:71], v[28:29], v[28:29]
	v_add_f32_e32 v0, v91, v0
	v_add_f32_e32 v37, v87, v37
	v_pk_mul_f32 v[80:81], v[26:27], v[26:27]
	v_pk_mul_f32 v[18:19], v[32:33], v[32:33]
	v_add_f32_e32 v0, v37, v0
	v_add_f32_e32 v37, v70, v71
	v_pk_mul_f32 v[20:21], v[30:31], v[30:31]
	v_add_f32_e32 v37, v80, v37
	v_add_f32_e32 v18, v18, v19
	v_add_f32_e32 v37, v81, v37
	v_add_f32_e32 v18, v20, v18
	v_add_f32_e32 v0, v37, v0
	v_add_f32_e32 v18, v21, v18
	v_add_f32_e32 v0, v18, v0
	s_nop 1
	v_add_f32_dpp v0, v0, v0 quad_perm:[1,0,3,2] row_mask:0xf bank_mask:0xf bound_ctrl:1
	s_nop 1
	v_add_f32_dpp v0, v0, v0 quad_perm:[2,3,0,1] row_mask:0xf bank_mask:0xf bound_ctrl:1
	s_nop 1
	v_add_f32_dpp v0, v0, v0 row_half_mirror row_mask:0xf bank_mask:0xf bound_ctrl:1
	s_nop 1
	v_add_f32_dpp v0, v0, v0 row_mirror row_mask:0xf bank_mask:0xf bound_ctrl:1
	v_mov_b32_e32 v18, v0
	s_nop 1
	v_permlane16_swap_b32_e32 v0, v18
	v_add_f32_e32 v0, v0, v18
	v_mov_b32_e32 v18, v0
	s_nop 1
	v_permlane32_swap_b32_e32 v0, v18
	v_add_f32_e32 v0, v0, v18
	v_fmamk_f32 v0, v0, 0x3a800000, v210
	v_cmp_gt_f32_e64 s[6:7], s2, v0
	v_mul_f32_e32 v18, 0x4b800000, v0
	s_nop 0
	v_cndmask_b32_e64 v0, v0, v18, s[6:7]
	v_rsq_f32_e32 v0, v0
	s_nop 0
	v_mul_f32_e32 v18, 0x45800000, v0
	v_cndmask_b32_e64 v64, v0, v18, s[6:7]
	v_pk_mul_f32 v[18:19], v[82:83], v[64:65] op_sel_hi:[1,0]
	v_pk_mul_f32 v[20:21], v[84:85], v[64:65] op_sel_hi:[1,0]
	s_waitcnt vmcnt(0)
	v_pk_fma_f32 v[18:19], v[66:67], v[18:19], v[76:77]
	v_pk_fma_f32 v[20:21], v[68:69], v[20:21], v[78:79]
	s_and_saveexec_b64 s[6:7], vcc
	s_cbranch_execz .LBB0_1316
	v_lshlrev_b32_e32 v0, 2, v36
	v_lshl_add_u64 v[66:67], v[74:75], 0, v[0:1]
	global_store_dwordx4 v[66:67], v[18:21], off nt
.LBB0_1316:
	s_or_b64 exec, exec, s[6:7]
	global_load_dwordx4 v[66:69], v[38:39], off offset:1024
	global_load_dwordx4 v[76:79], v[40:41], off offset:1024
	v_mov_b32_e32 v65, v64
	v_pk_mul_f32 v[24:25], v[24:25], v[64:65]
	v_pk_mul_f32 v[70:71], v[22:23], v[64:65]
	s_waitcnt vmcnt(0)
	v_pk_fma_f32 v[22:23], v[24:25], v[66:67], v[76:77]
	v_pk_fma_f32 v[24:25], v[70:71], v[68:69], v[78:79]
	s_and_saveexec_b64 s[6:7], vcc
	s_cbranch_execz .LBB0_1318
	v_lshlrev_b32_e32 v0, 2, v36
	v_lshl_add_u64 v[66:67], v[74:75], 0, v[0:1]
	global_store_dwordx4 v[66:67], v[22:25], off offset:1024 nt
.LBB0_1318:
	s_or_b64 exec, exec, s[6:7]
	global_load_dwordx4 v[66:69], v[38:39], off offset:2048
	global_load_dwordx4 v[76:79], v[40:41], off offset:2048
	v_pk_mul_f32 v[28:29], v[28:29], v[64:65]
	v_pk_mul_f32 v[70:71], v[26:27], v[64:65]
	s_waitcnt vmcnt(0)
	v_pk_fma_f32 v[26:27], v[28:29], v[66:67], v[76:77]
	v_pk_fma_f32 v[28:29], v[70:71], v[68:69], v[78:79]
	s_and_saveexec_b64 s[6:7], vcc
	s_cbranch_execz .LBB0_1320
	v_lshlrev_b32_e32 v0, 2, v36
	v_lshl_add_u64 v[66:67], v[74:75], 0, v[0:1]
	global_store_dwordx4 v[66:67], v[26:29], off offset:2048 nt
.LBB0_1320:
	s_or_b64 exec, exec, s[6:7]
	global_load_dwordx4 v[66:69], v[38:39], off offset:3072
	global_load_dwordx4 v[76:79], v[40:41], off offset:3072
	v_pk_mul_f32 v[32:33], v[32:33], v[64:65]
	v_pk_mul_f32 v[64:65], v[30:31], v[64:65]
	s_waitcnt vmcnt(0)
	v_pk_fma_f32 v[30:31], v[32:33], v[66:67], v[76:77]
	v_pk_fma_f32 v[32:33], v[64:65], v[68:69], v[78:79]
	s_and_saveexec_b64 s[6:7], vcc
	s_cbranch_execz .LBB0_1322
	v_lshlrev_b32_e32 v0, 2, v36
	v_lshl_add_u64 v[64:65], v[74:75], 0, v[0:1]
	global_store_dwordx4 v[64:65], v[30:33], off offset:3072 nt
